# attention loop head shifted by 8 s_nop (code placement test)
# speedup vs baseline: 1.0011x; 1.0007x over previous
;   #define DMA_K(t,s3) glds16(ksrc+(long)(t)*KVBLK*DM,(unsigned)__builtin_amdgcn_readfirstlane(kdst+(s3)*SLOTB))
;   #define DMA_V(t,s3) do{ const unsigned vd_=(unsigned)__builtin_amdgcn_readfirstlane(vdst+(s3)*VSLOTB); glds16(vsrc+(long)(t)*KVBLK*DM,vd_); glds16(vsrc+(long)(t)*KVBLK*DM+64,(unsigned)__builtin_amdgcn_readfirstlane(vd_+8192)); }while(0)
; template<int THRL> __device__ __forceinline__ void attn_unit(int qb,const bf16*Q,const bf16*__restrict__ K,const bf16*__restrict__ V,bf16*O,char*shm){
;     ...
;   for(int t=0;t<NT;++t){
;     if(t+2<NT){DMA_K(t+2,c2);DMA_V(t+2,c2);}
;     bf16x8 kf[8]; kload8(kf,kp0+c0*SLOTB);
.LBB0_366:
	s_lshl_b32 s14, s34, 14
	v_add_u32_e32 v193, s14, v190
	s_nop 0
	s_nop 0
	s_nop 0
	s_nop 0
	s_nop 0
	s_nop 0
	s_nop 0
	s_nop 0
